# v108 + attention tile loop laid out for one taken branch per key tile: head mask out of line, zero-reference chain behind the dispatch with its own tail P*V block and loop latch
# baseline (speedup 1.0000x reference)
; __device__ __forceinline__ void apply_mask(bool MASK, f32x16& s0, int kvr, int r, int h) {
;     if (MASK) {
;         asm volatile("" ::: "memory");
;         const int d = r - 4 * h - kvr;
; #pragma unroll
;         for (int i = 0; i < 16; ++i) { if (((i & 3) + 8 * (i >> 2)) > d) s0[i] = -INFINITY; }
;     }
; }
; __device__ __forceinline__ void tile_body(bool MASK, const ATT_LAS unsigned char* kb, const ATT_LAS unsigned char* vb, const ATT_LAS unsigned char* qbase, const int (&kaddr)[4], const int (&vaddr)[2], ...
;     ...
;     qk_issue<false>(Sa, kb, qbase, kaddr);
;     apply_mask(MASK, Sa, kvrel, r, h); ls = l1;
.Lhead_mask:
	v_cmp_gt_i32_e64 s[34:35], 25, v214
	v_cmp_gt_i32_e64 s[28:29], 24, v214
	s_and_b64 s[34:35], vcc, s[34:35]
	v_cmp_gt_i32_e64 s[26:27], 19, v214
	s_and_b64 s[28:29], s[34:35], s[28:29]
	v_cmp_gt_i32_e64 s[24:25], 18, v214
	s_and_b64 s[26:27], s[28:29], s[26:27]
	v_cmp_gt_i32_e64 s[22:23], 17, v214
	s_and_b64 s[24:25], s[26:27], s[24:25]
	v_cmp_gt_i32_e64 s[20:21], 16, v214
	s_and_b64 s[22:23], s[24:25], s[22:23]
	v_cmp_gt_i32_e64 s[18:19], 11, v214
	s_and_b64 s[20:21], s[22:23], s[20:21]
	v_cmp_gt_i32_e64 s[16:17], 10, v214
	s_and_b64 s[18:19], s[20:21], s[18:19]
	v_cmp_gt_i32_e64 s[14:15], 9, v214
	s_and_b64 s[16:17], s[18:19], s[16:17]
	v_cmp_gt_i32_e64 s[12:13], 8, v214
	s_and_b64 s[14:15], s[16:17], s[14:15]
	v_cmp_gt_i32_e64 s[10:11], 3, v214
	s_and_b64 s[12:13], s[14:15], s[12:13]
	v_cmp_gt_i32_e64 s[8:9], 2, v214
	s_and_b64 s[10:11], s[12:13], s[10:11]
	v_cmp_gt_i32_e64 s[6:7], 1, v214
	s_and_b64 s[8:9], s[10:11], s[8:9]
	v_cmp_gt_i32_e64 s[4:5], 0, v214
	s_and_b64 s[6:7], s[8:9], s[6:7]
	s_and_b64 s[4:5], s[6:7], s[4:5]
	v_cndmask_b32_e64 v183, v183, v17, s[34:35]
	v_cndmask_b32_e64 v182, v182, v17, s[28:29]
	v_cndmask_b32_e64 v181, v181, v17, s[26:27]
	v_cndmask_b32_e64 v180, v180, v17, s[24:25]
	v_cndmask_b32_e64 v179, v179, v17, s[22:23]
	v_cndmask_b32_e64 v178, v178, v17, s[20:21]
	v_cndmask_b32_e64 v177, v177, v17, s[18:19]
	v_cndmask_b32_e64 v176, v176, v17, s[16:17]
	v_cndmask_b32_e64 v175, v175, v17, s[14:15]
	v_cndmask_b32_e64 v174, v174, v17, s[12:13]
	v_cndmask_b32_e64 v173, v173, v17, s[10:11]
	v_cndmask_b32_e64 v172, v172, v17, s[8:9]
	v_cndmask_b32_e64 v171, v171, v17, s[6:7]
	v_cndmask_b32_e64 v170, v170, v17, s[4:5]
	v_cndmask_b32_e32 v184, v184, v17, vcc
	v_cmp_gt_i32_e32 vcc, 27, v214
	s_and_saveexec_b64 s[4:5], vcc
	v_mov_b32_e32 v185, s31
	s_or_b64 exec, exec, s[4:5]
	s_branch .LBB0_296

; #define ATT_LAS __attribute__((address_space(3)))
; __device__ __forceinline__ void tile_body(bool MASK, const ATT_LAS unsigned char* kb, const ATT_LAS unsigned char* vb, const ATT_LAS unsigned char* qbase, const int (&kaddr)[4], const int (&vaddr)[2], ...
;     ...
;     qk_issue<false>(Sa, kb, qbase, kaddr);
;     apply_mask(MASK, Sa, kvrel, r, h); ls = l1;
; __device__ __forceinline__ void attn_unit(ATT_LAS unsigned char* lds, const bf16_t* Qg, const bf16_t* Kg, const bf16_t* Vg, bf16_t* Og, int b, int head, int qb, float lam, const float* subg) {
;     ...
;         const int kvrel = 64 * t - q0 - 32 * wq;
;         if (kvrel <= 31) {
;             const ATT_LAS unsigned char* kb = lds + KBUF + buf * 16384;
;             const ATT_LAS unsigned char* vb = lds + VBUF + buf * 16384;
;             tile_body(kvrel + 63 > 0, kb, vb, qbase, kaddr, vaddr, O1, O2, m1, m2, l1, l2, kvrel, r, h, wsf);
.LBB0_291:
	s_cmp_gt_i32 s80, 31
	s_cbranch_scc1 .Ldma_skip
	s_lshl_b32 s4, s4, 14
	s_add_i32 s81, s4, 0
	v_add_u32_e32 v248, s81, v209
	v_add_u32_e32 v249, s81, v210
	v_add_u32_e32 v250, s81, v211
	v_add_u32_e32 v251, s81, v212
	v_add_u32_e32 v216, s81, v203
	ds_read_b128 v[2:5], v216
	ds_read_b128 v[6:9], v217
	v_add_u32_e32 v218, s81, v204
	v_add_u32_e32 v220, s81, v205
	v_add_u32_e32 v222, s81, v206
	s_waitcnt lgkmcnt(0)
	v_mfma_f32_32x32x16_bf16 v[170:185], v[2:5], v[6:9], 0
	ds_read_b128 v[2:5], v218
	ds_read_b128 v[6:9], v219
	s_cmpk_gt_i32 s80, 0xffc1
	s_cselect_b64 s[36:37], -1, 0
	s_cmpk_lt_i32 s80, 0xffc2
	v_cmp_gt_i32_e32 vcc, 26, v214
	s_waitcnt lgkmcnt(0)
	v_mfma_f32_32x32x16_bf16 v[170:185], v[2:5], v[6:9], v[170:185]
	ds_read_b128 v[2:5], v220
	ds_read_b128 v[6:9], v221
	s_waitcnt lgkmcnt(0)
	v_mfma_f32_32x32x16_bf16 v[170:185], v[2:5], v[6:9], v[170:185]
	ds_read_b128 v[2:5], v222
	ds_read_b128 v[6:9], v223
	s_waitcnt lgkmcnt(0)
	v_mfma_f32_32x32x16_bf16 v[170:185], v[2:5], v[6:9], v[170:185]
	s_cbranch_scc0 .Lhead_mask

; __device__ __forceinline__ void tile_body(bool MASK, const ATT_LAS unsigned char* kb, const ATT_LAS unsigned char* vb, const ATT_LAS unsigned char* qbase, const int (&kaddr)[4], const int (&vaddr)[2], ...
;     f32x16 Sa, Sb; u32x4 pkA[2], pkB[2]; float ls, sm;
;     qk_issue<false>(Sa, kb, qbase, kaddr);
;     apply_mask(MASK, Sa, kvrel, r, h); ls = l1;
;     sm = step_fused<false, true, true>(Sa, m1, l1, pkA, O1, pkA, vb, vaddr, Sb, kb, qbase, kaddr);
;     if (__any(!(sm <= GUARD))) slow_step<false>(MASK, Sa, kb, qbase, kaddr, vaddr, O1, m1, l1, ls, kvrel, r, h, wsf, pkA);
.Ldma_s1:
	v_or_b32_e32 v252, v0, v215
	v_cmp_eq_u32_e32 vcc, 0, v252
	s_cmp_eq_u64 vcc, exec
	s_cbranch_scc0 .Lorig_296

; template <bool HAS_PV, bool HAS_QK, bool C1> ...
;     s16x4 vlo[2], vhi[2]; bf16x8 ka, qa;
;     if (HAS_PV) {
; #pragma unroll
;         for (int u = 0; u < 2; ++u) { vlo[u] = vtr(vb + vaddr[0] + u * 512); vhi[u] = vtr(vb + vaddr[1] + u * 512); } }
;     if (HAS_QK) { const int ad = C1 ? sub1(kaddr[0]) : kaddr[0]; ka = *(const ATT_LAS bf16x8*)(kb + ad); qa = *(const ATT_LAS bf16x8*)(qb_ + ad);
; #pragma unroll
;         for (int i = 0; i < 16; ++i) Snext[i] = 0.f; }
;     float sa = 0.f, sb = 0.f;
; #pragma unroll
;     for (int g = 0; g < 4; ++g) {
;         s16x4 nlo[2], nhi[2]; bf16x8 nk, nq;
;         if (g < 3) {
;             if (HAS_PV) {
; #pragma unroll
;                 for (int u = 0; u < 2; ++u) { const int off = (2 * ((g + 1) & 1) + u) * 512 + ((g + 1) >> 1) * 4096; nlo[u] = vtr(vb + vaddr[0] + off); nhi[u] = vtr(vb + vaddr[1] + off); } }
;             if (HAS_QK) { const int ad = C1 ? sub1(kaddr[g + 1]) : kaddr[g + 1]; nk = *(const ATT_LAS bf16x8*)(kb + ad); nq = *(const ATT_LAS bf16x8*)(qb_ + ad); }
;         }
;         if (HAS_PV) { const bf16x8 pa = __builtin_bit_cast(bf16x8, pkin[g >> 1]);
; #pragma unroll
;             for (int u = 0; u < 2; ++u) { const bf16x8 vf = __builtin_shufflevector(vlo[u], vhi[u], 0, 1, 2, 3, 4, 5, 6, 7); Opv[2 * (g & 1) + u] = ATT_MFMA(pa, vf, Opv[2 * (g & 1) + u]); } }
;         if (HAS_QK) Snext = ATT_MFMA(ka, qa, Snext);
; #pragma unroll
;         for (int e = 4 * g; e < 4 * g + 4; e += 2) { Scur[e] = __builtin_amdgcn_exp2f(Scur[e] - m); Scur[e + 1] = __builtin_amdgcn_exp2f(Scur[e + 1] - m); sa += Scur[e]; sb += Scur[e + 1]; }
;         if (g & 1) pkout[g >> 1] = (u32x4){cvtpk(Scur[4 * g - 4], Scur[4 * g - 3]), cvtpk(Scur[4 * g - 2], Scur[4 * g - 1]), cvtpk(Scur[4 * g], Scur[4 * g + 1]), cvtpk(Scur[4 * g + 2], Scur[4 * g + 3])};
;         if (g < 3) {
;             if (HAS_PV) {
; #pragma unroll
;                 for (int u = 0; u < 2; ++u) { vlo[u] = nlo[u]; vhi[u] = nhi[u]; } }
;             if (HAS_QK) { ka = nk; qa = nq; }
;         }
;         __builtin_amdgcn_sched_barrier(0);
;     }
;     l += sa + sb;
;     return sa + sb;
; }
; __device__ __forceinline__ void pv_issue(f32x16 (&O)[4], const u32x4 (&pk)[2], const ATT_LAS unsigned char* vb, const int (&vaddr)[2]) {
; #pragma unroll
;     for (int s_ = 0; s_ < 2; ++s_) { const bf16x8 pa = __builtin_bit_cast(bf16x8, pk[s_]);
; #pragma unroll
.Lns_341:
	ds_read_b64_tr_b16 v[8:9], v178 offset:43008
	ds_read_b64_tr_b16 v[6:7], v179 offset:40960
	ds_read_b64_tr_b16 v[146:147], v179 offset:41472
	ds_read_b64_tr_b16 v[150:151], v179 offset:41984
	ds_read_b64_tr_b16 v[154:155], v179 offset:42496
	ds_read_b64_tr_b16 v[148:149], v178 offset:43520
	ds_read_b64_tr_b16 v[152:153], v178 offset:44032
	ds_read_b64_tr_b16 v[156:157], v178 offset:44544
	s_waitcnt lgkmcnt(6)
	v_mfma_f32_32x32x16_bf16 v[34:49], v[2:5], v[6:9], v[34:49]
	v_exp_f32_e32 v15, v162
	v_exp_f32_e32 v14, v163
	v_exp_f32_e32 v163, v164
	s_waitcnt lgkmcnt(2)
	v_mfma_f32_32x32x16_bf16 v[50:65], v[2:5], v[146:149], v[50:65]
	v_exp_f32_e32 v162, v165
	s_waitcnt lgkmcnt(1)
	v_mfma_f32_32x32x16_bf16 v[66:81], v[2:5], v[150:153], v[66:81]
	ds_read_b64_tr_b16 v[146:147], v179 offset:45056
	ds_read_b64_tr_b16 v[148:149], v178 offset:47104
	ds_read_b64_tr_b16 v[160:161], v178 offset:47616
	ds_read_b64_tr_b16 v[158:159], v179 offset:45568
	v_exp_f32_e32 v165, v166
	v_exp_f32_e32 v164, v167
	v_exp_f32_e32 v167, v168
	s_waitcnt lgkmcnt(4)
	v_mfma_f32_32x32x16_bf16 v[82:97], v[2:5], v[154:157], v[82:97]
	v_exp_f32_e32 v166, v169
	v_cvt_pk_bf16_f32 v6, v15, v14
	v_cvt_pk_bf16_f32 v7, v163, v162
	v_cvt_pk_bf16_f32 v8, v165, v164
	v_cvt_pk_bf16_f32 v9, v167, v166
	s_waitcnt lgkmcnt(2)
	v_mfma_f32_32x32x16_bf16 v[34:49], v[10:13], v[146:149], v[34:49]
	ds_read_b64_tr_b16 v[2:3], v179 offset:46080
	ds_read_b64_tr_b16 v[4:5], v178 offset:48128
	ds_read_b64_tr_b16 v[152:153], v178 offset:48640
	ds_read_b64_tr_b16 v[150:151], v179 offset:46592
	v_exp_f32_e32 v147, v170
	v_exp_f32_e32 v146, v171
	v_exp_f32_e32 v149, v172
	s_waitcnt lgkmcnt(4)
	v_mfma_f32_32x32x16_bf16 v[50:65], v[10:13], v[158:161], v[50:65]
	v_exp_f32_e32 v148, v173
	s_waitcnt lgkmcnt(2)
	v_mfma_f32_32x32x16_bf16 v[66:81], v[10:13], v[2:5], v[66:81]
	v_exp_f32_e32 v155, v174
	v_exp_f32_e32 v154, v175
	v_exp_f32_e32 v157, v176
	s_waitcnt lgkmcnt(0)
	v_mfma_f32_32x32x16_bf16 v[82:97], v[10:13], v[150:153], v[82:97]
	v_add_f32_e64 v10, v162, v14
	v_add_f32_e64 v11, v163, v15
	v_exp_f32_e32 v156, v177
	v_add_f32_e32 v10, v164, v10
	v_add_f32_e32 v11, v165, v11
	v_cvt_pk_bf16_f32 v2, v147, v146
	v_cvt_pk_bf16_f32 v3, v149, v148
	v_cvt_pk_bf16_f32 v4, v155, v154
	v_cvt_pk_bf16_f32 v5, v157, v156
	v_add_f32_e32 v10, v166, v10
	v_add_f32_e32 v11, v167, v11
	v_add_f32_e32 v10, v146, v10
	v_add_f32_e32 v11, v147, v11
	v_add_f32_e32 v10, v148, v10
	v_add_f32_e32 v11, v149, v11
	v_add_f32_e32 v10, v154, v10
	v_add_f32_e32 v11, v155, v11
	v_add_f32_e32 v10, v156, v10
	v_add_f32_e32 v11, v157, v11
	v_add_f32_e32 v10, v10, v11
	v_cmp_nge_f32_e32 vcc, s58, v10
	s_cbranch_vccnz .Lslow_4
	v_add_f32_e32 v224, v181, v10
	ds_read_b64_tr_b16 v[12:13], v178 offset:43008
	ds_read_b64_tr_b16 v[10:11], v179 offset:40960
	ds_read_b64_tr_b16 v[146:147], v179 offset:41472
	ds_read_b64_tr_b16 v[150:151], v179 offset:41984
	ds_read_b64_tr_b16 v[154:155], v179 offset:42496
	ds_read_b64_tr_b16 v[148:149], v178 offset:43520
	ds_read_b64_tr_b16 v[152:153], v178 offset:44032
	ds_read_b64_tr_b16 v[156:157], v178 offset:44544
	s_waitcnt lgkmcnt(6)
	v_mfma_f32_32x32x16_bf16 v[130:145], v[6:9], v[10:13], v[130:145]
	s_waitcnt lgkmcnt(2)
	v_mfma_f32_32x32x16_bf16 v[114:129], v[6:9], v[146:149], v[114:129]
	s_waitcnt lgkmcnt(1)
	v_mfma_f32_32x32x16_bf16 v[98:113], v[6:9], v[150:153], v[98:113]
	s_waitcnt lgkmcnt(0)
	v_mfma_f32_32x32x16_bf16 v[18:33], v[6:9], v[154:157], v[18:33]
	ds_read_b64_tr_b16 v[8:9], v178 offset:47104
	ds_read_b64_tr_b16 v[6:7], v179 offset:45056
	ds_read_b64_tr_b16 v[10:11], v179 offset:45568
	ds_read_b64_tr_b16 v[146:147], v179 offset:46080
	ds_read_b64_tr_b16 v[150:151], v179 offset:46592
	ds_read_b64_tr_b16 v[12:13], v178 offset:47616
	ds_read_b64_tr_b16 v[148:149], v178 offset:48128
	ds_read_b64_tr_b16 v[152:153], v178 offset:48640
	s_waitcnt lgkmcnt(6)
	v_mfma_f32_32x32x16_bf16 v[130:145], v[2:5], v[6:9], v[130:145]
	s_waitcnt lgkmcnt(2)
	v_mfma_f32_32x32x16_bf16 v[114:129], v[2:5], v[10:13], v[114:129]
	s_waitcnt lgkmcnt(1)
	v_mfma_f32_32x32x16_bf16 v[98:113], v[2:5], v[146:149], v[98:113]
	s_waitcnt lgkmcnt(0)
	v_mfma_f32_32x32x16_bf16 v[18:33], v[2:5], v[150:153], v[18:33]
	s_add_i32 s80, s80, 64
	s_add_u32 s94, s94, 0x20000
	s_addc_u32 s95, s95, 0
	s_waitcnt vmcnt(0)
	s_add_u32 s92, s92, 0x20000
	s_addc_u32 s93, s93, 0
	s_cmp_eq_u32 s76, s79
	v_subrev_u32_e32 v214, 64, v214
	s_barrier
	s_cbranch_scc0 .LBB0_289
	s_branch .LBB0_352

; #define ATT_LAS __attribute__((address_space(3)))
; __device__ __forceinline__ unsigned cvtpk(float lo, float hi) { unsigned r; asm volatile("v_cvt_pk_bf16_f32 %0, %1, %2" : "=v"(r) : "v"(lo), "v"(hi)); return r; }
; template <bool HAS_PV, bool HAS_QK, bool C1> ...
;     s16x4 vlo[2], vhi[2]; bf16x8 ka, qa;
;     if (HAS_PV) {
; #pragma unroll
;         for (int u = 0; u < 2; ++u) { vlo[u] = vtr(vb + vaddr[0] + u * 512); vhi[u] = vtr(vb + vaddr[1] + u * 512); } }
;     if (HAS_QK) { const int ad = C1 ? sub1(kaddr[0]) : kaddr[0]; ka = *(const ATT_LAS bf16x8*)(kb + ad); qa = *(const ATT_LAS bf16x8*)(qb_ + ad);
; #pragma unroll
;         for (int i = 0; i < 16; ++i) Snext[i] = 0.f; }
;     float sa = 0.f, sb = 0.f;
; #pragma unroll
;     for (int g = 0; g < 4; ++g) {
;         s16x4 nlo[2], nhi[2]; bf16x8 nk, nq;
;         if (g < 3) {
;             if (HAS_PV) {
; #pragma unroll
;                 for (int u = 0; u < 2; ++u) { const int off = (2 * ((g + 1) & 1) + u) * 512 + ((g + 1) >> 1) * 4096; nlo[u] = vtr(vb + vaddr[0] + off); nhi[u] = vtr(vb + vaddr[1] + off); } }
;             if (HAS_QK) { const int ad = C1 ? sub1(kaddr[g + 1]) : kaddr[g + 1]; nk = *(const ATT_LAS bf16x8*)(kb + ad); nq = *(const ATT_LAS bf16x8*)(qb_ + ad); }
;         }
;         if (HAS_PV) { const bf16x8 pa = __builtin_bit_cast(bf16x8, pkin[g >> 1]);
; #pragma unroll
;             for (int u = 0; u < 2; ++u) { const bf16x8 vf = __builtin_shufflevector(vlo[u], vhi[u], 0, 1, 2, 3, 4, 5, 6, 7); Opv[2 * (g & 1) + u] = ATT_MFMA(pa, vf, Opv[2 * (g & 1) + u]); } }
;         if (HAS_QK) Snext = ATT_MFMA(ka, qa, Snext);
; #pragma unroll
;         for (int e = 4 * g; e < 4 * g + 4; e += 2) { Scur[e] = __builtin_amdgcn_exp2f(Scur[e] - m); Scur[e + 1] = __builtin_amdgcn_exp2f(Scur[e + 1] - m); sa += Scur[e]; sb += Scur[e + 1]; }
;         if (g & 1) pkout[g >> 1] = (u32x4){cvtpk(Scur[4 * g - 4], Scur[4 * g - 3]), cvtpk(Scur[4 * g - 2], Scur[4 * g - 1]), cvtpk(Scur[4 * g], Scur[4 * g + 1]), cvtpk(Scur[4 * g + 2], Scur[4 * g + 3])};
;         if (g < 3) {
;             if (HAS_PV) {
; #pragma unroll
;                 for (int u = 0; u < 2; ++u) { vlo[u] = nlo[u]; vhi[u] = nhi[u]; } }
;             if (HAS_QK) { ka = nk; qa = nq; }
;         }
;         __builtin_amdgcn_sched_barrier(0);
;     }
;     l += sa + sb;
;     return sa + sb;
; }
.Lorig_296:
	ds_read_b128 v[2:5], v248
	ds_read_b128 v[6:9], v244
	s_nop 8
	v_sub_f32_e32 v16, v172, v0
	ds_read_b128 v[10:13], v249
	ds_read_b128 v[146:149], v245
	v_sub_f32_e32 v14, v170, v0
	v_exp_f32_e32 v15, v14
	v_sub_f32_e32 v14, v171, v0
	v_exp_f32_e32 v155, v16
	v_sub_f32_e32 v16, v173, v0
	s_waitcnt lgkmcnt(2)
	v_mfma_f32_32x32x16_bf16 v[158:173], v[2:5], v[6:9], 0
	v_exp_f32_e32 v14, v14
	v_exp_f32_e32 v154, v16
	s_waitcnt lgkmcnt(0)
	v_mfma_f32_32x32x16_bf16 v[158:173], v[10:13], v[146:149], v[158:173]
	ds_read_b128 v[6:9], v250
	ds_read_b128 v[150:153], v246
	v_sub_f32_e32 v2, v174, v0
	v_exp_f32_e32 v157, v2
	v_sub_f32_e32 v2, v175, v0
	v_exp_f32_e32 v156, v2
	v_sub_f32_e32 v2, v176, v0
	v_exp_f32_e32 v175, v2
	v_sub_f32_e32 v2, v177, v0
	v_exp_f32_e32 v174, v2
	v_cvt_pk_bf16_f32 v2, v15, v14
	v_cvt_pk_bf16_f32 v3, v155, v154
	v_cvt_pk_bf16_f32 v4, v157, v156
	v_cvt_pk_bf16_f32 v5, v175, v174
	s_waitcnt lgkmcnt(0)
	v_mfma_f32_32x32x16_bf16 v[158:173], v[6:9], v[150:153], v[158:173]
	ds_read_b128 v[10:13], v251
	ds_read_b128 v[146:149], v247
	v_sub_f32_e32 v16, v178, v0
	v_exp_f32_e32 v177, v16
	v_sub_f32_e32 v16, v179, v0
	v_exp_f32_e32 v176, v16
	v_sub_f32_e32 v16, v180, v0
	v_exp_f32_e32 v179, v16
	v_sub_f32_e32 v16, v181, v0
	v_exp_f32_e32 v178, v16
	v_sub_f32_e32 v6, v182, v0
	s_waitcnt lgkmcnt(0)
	v_mfma_f32_32x32x16_bf16 v[158:173], v[10:13], v[146:149], v[158:173]
	v_add_f32_e64 v14, v14, 0
	v_add_f32_e64 v15, v15, 0
	v_exp_f32_e32 v7, v6
	v_sub_f32_e32 v6, v183, v0
	v_sub_f32_e32 v8, v184, v0
	v_pk_add_f32 v[14:15], v[154:155], v[14:15]
	v_exp_f32_e32 v6, v6
	v_exp_f32_e32 v9, v8
	v_sub_f32_e32 v8, v185, v0
	v_pk_add_f32 v[14:15], v[156:157], v[14:15]
	v_exp_f32_e32 v8, v8
	v_pk_add_f32 v[14:15], v[174:175], v[14:15]
	v_cvt_pk_bf16_f32 v10, v177, v176
	v_cvt_pk_bf16_f32 v11, v179, v178
	v_cvt_pk_bf16_f32 v12, v7, v6
	v_cvt_pk_bf16_f32 v13, v9, v8
	s_nop 0
	v_pk_add_f32 v[14:15], v[176:177], v[14:15]
	s_nop 0
	v_pk_add_f32 v[14:15], v[178:179], v[14:15]
	s_nop 0
	v_pk_add_f32 v[6:7], v[6:7], v[14:15]
	s_nop 0
	v_pk_add_f32 v[6:7], v[8:9], v[6:7]
	s_nop 0
	v_add_f32_e32 v6, v6, v7
	v_cndmask_b32_e64 v7, 0, 1, s[36:37]
	v_cmp_nge_f32_e32 vcc, s58, v6
	v_cmp_ne_u32_e64 s[4:5], 1, v7
	s_cbranch_vccz .LBB0_305
